# L2 carry-in rewritten: all chunk-aggregate loads of both directions pipelined, exec-masked loads and compose (only needed entries fetched)
# speedup vs baseline: 1.0653x; 1.0122x over previous
.Ll2ci_begin:
	s_mov_b64 s[26:27], exec
	v_mov_b32_e32 v245, v120
	s_mul_i32 s28, s49, 0x22000
	s_add_u32 s76, s38, s28
	s_addc_u32 s77, s39, 0
	s_add_u32 s78, s70, s28
	s_addc_u32 s79, s71, 0
	v_lshlrev_b32_e32 v83, 2, v18
	v_add_u32_e32 v92, 0x22000, v83
	v_min_i32_e32 v52, 0x43, v72
	v_min_i32_e32 v53, 0x43, v74
	v_min_i32_e32 v54, 0x43, v76
	v_min_i32_e32 v55, 0x43, v78
	v_min_i32_e32 v94, 0x43, v81
	v_lshl_add_u32 v52, v52, 11, v83
	v_lshl_add_u32 v53, v53, 11, v83
	v_lshl_add_u32 v54, v54, 11, v83
	v_lshl_add_u32 v55, v55, 11, v83
	v_lshl_add_u32 v94, v94, 11, v83
	v_min_i32_e32 v95, 0x43, v73
	v_min_i32_e32 v96, 0x43, v75
	v_min_i32_e32 v98, 0x43, v77
	v_min_i32_e32 v99, 0x43, v79
	v_min_i32_e32 v100, 0x43, v80
	v_lshl_add_u32 v95, v95, 11, v92
	v_lshl_add_u32 v96, v96, 11, v92
	v_lshl_add_u32 v98, v98, 11, v92
	v_lshl_add_u32 v99, v99, 11, v92
	v_lshl_add_u32 v100, v100, 11, v92
	s_mov_b64 exec, s[8:9]
	global_load_dwordx4 v[36:39], v52, s[76:77] offset:0
	global_load_dwordx4 v[84:87], v52, s[78:79] offset:0
	global_load_dwordx4 v[40:43], v52, s[76:77] offset:64
	global_load_dwordx4 v[88:91], v52, s[78:79] offset:64
	global_load_dwordx4 v[44:47], v52, s[76:77] offset:128
	global_load_dwordx4 v[102:105], v52, s[78:79] offset:128
	global_load_dwordx4 v[48:51], v52, s[76:77] offset:192
	global_load_dwordx4 v[106:109], v52, s[78:79] offset:192
	s_mov_b64 exec, s[26:27]
	s_mov_b64 exec, s[10:11]
	global_load_dwordx4 v[110:113], v53, s[76:77] offset:0
	global_load_dwordx4 v[126:129], v53, s[78:79] offset:0
	global_load_dwordx4 v[114:117], v53, s[76:77] offset:64
	global_load_dwordx4 v[130:133], v53, s[78:79] offset:64
	global_load_dwordx4 v[118:121], v53, s[76:77] offset:128
	global_load_dwordx4 v[134:137], v53, s[78:79] offset:128
	global_load_dwordx4 v[122:125], v53, s[76:77] offset:192
	global_load_dwordx4 v[138:141], v53, s[78:79] offset:192
	s_mov_b64 exec, s[26:27]
	s_mov_b64 exec, s[12:13]
	global_load_dwordx4 v[142:145], v54, s[76:77] offset:0
	global_load_dwordx4 v[158:161], v54, s[78:79] offset:0
	global_load_dwordx4 v[146:149], v54, s[76:77] offset:64
	global_load_dwordx4 v[162:165], v54, s[78:79] offset:64
	global_load_dwordx4 v[150:153], v54, s[76:77] offset:128
	global_load_dwordx4 v[166:169], v54, s[78:79] offset:128
	global_load_dwordx4 v[154:157], v54, s[76:77] offset:192
	global_load_dwordx4 v[170:173], v54, s[78:79] offset:192
	s_mov_b64 exec, s[26:27]
	s_mov_b64 exec, s[14:15]
	global_load_dwordx4 v[174:177], v55, s[76:77] offset:0
	global_load_dwordx4 v[192:195], v55, s[78:79] offset:0
	global_load_dwordx4 v[178:181], v55, s[76:77] offset:64
	global_load_dwordx4 v[196:199], v55, s[78:79] offset:64
	global_load_dwordx4 v[182:185], v55, s[76:77] offset:128
	global_load_dwordx4 v[200:203], v55, s[78:79] offset:128
	global_load_dwordx4 v[186:189], v55, s[76:77] offset:192
	global_load_dwordx4 v[204:207], v55, s[78:79] offset:192
	s_mov_b64 exec, s[26:27]
	s_mov_b64 exec, s[16:17]
	global_load_dwordx4 v[208:211], v94, s[76:77] offset:0
	global_load_dwordx4 v[224:227], v94, s[78:79] offset:0
	global_load_dwordx4 v[212:215], v94, s[76:77] offset:64
	global_load_dwordx4 v[234:237], v94, s[78:79] offset:64
	global_load_dwordx4 v[216:219], v94, s[76:77] offset:128
	global_load_dwordx4 v[246:249], v94, s[78:79] offset:128
	global_load_dwordx4 v[220:223], v94, s[76:77] offset:192
	global_load_dwordx4 v[250:253], v94, s[78:79] offset:192
	s_mov_b64 exec, s[26:27]
	s_waitcnt vmcnt(32)
	v_cndmask_b32_e64 v56, 1.0, v36, s[8:9]
	v_cndmask_b32_e64 v2, 0, v84, s[8:9]
	v_cndmask_b32_e64 v57, 1.0, v37, s[8:9]
	v_cndmask_b32_e64 v3, 0, v85, s[8:9]
	v_cndmask_b32_e64 v58, 1.0, v38, s[8:9]
	v_cndmask_b32_e64 v4, 0, v86, s[8:9]
	v_cndmask_b32_e64 v59, 1.0, v39, s[8:9]
	v_cndmask_b32_e64 v5, 0, v87, s[8:9]
	v_cndmask_b32_e64 v60, 1.0, v40, s[8:9]
	v_cndmask_b32_e64 v6, 0, v88, s[8:9]
	v_cndmask_b32_e64 v61, 1.0, v41, s[8:9]
	v_cndmask_b32_e64 v7, 0, v89, s[8:9]
	v_cndmask_b32_e64 v62, 1.0, v42, s[8:9]
	v_cndmask_b32_e64 v8, 0, v90, s[8:9]
	v_cndmask_b32_e64 v63, 1.0, v43, s[8:9]
	v_cndmask_b32_e64 v9, 0, v91, s[8:9]
	v_cndmask_b32_e64 v64, 1.0, v44, s[8:9]
	v_cndmask_b32_e64 v10, 0, v102, s[8:9]
	v_cndmask_b32_e64 v65, 1.0, v45, s[8:9]
	v_cndmask_b32_e64 v11, 0, v103, s[8:9]
	v_cndmask_b32_e64 v66, 1.0, v46, s[8:9]
	v_cndmask_b32_e64 v12, 0, v104, s[8:9]
	v_cndmask_b32_e64 v67, 1.0, v47, s[8:9]
	v_cndmask_b32_e64 v13, 0, v105, s[8:9]
	v_cndmask_b32_e64 v68, 1.0, v48, s[8:9]
	v_cndmask_b32_e64 v14, 0, v106, s[8:9]
	v_cndmask_b32_e64 v69, 1.0, v49, s[8:9]
	v_cndmask_b32_e64 v15, 0, v107, s[8:9]
	v_cndmask_b32_e64 v70, 1.0, v50, s[8:9]
	v_cndmask_b32_e64 v16, 0, v108, s[8:9]
	v_cndmask_b32_e64 v71, 1.0, v51, s[8:9]
	v_cndmask_b32_e64 v17, 0, v109, s[8:9]
	s_mov_b64 exec, s[18:19]
	global_load_dwordx4 v[36:39], v95, s[76:77] offset:0
	global_load_dwordx4 v[84:87], v95, s[78:79] offset:0
	global_load_dwordx4 v[40:43], v95, s[76:77] offset:64
	global_load_dwordx4 v[88:91], v95, s[78:79] offset:64
	global_load_dwordx4 v[44:47], v95, s[76:77] offset:128
	global_load_dwordx4 v[102:105], v95, s[78:79] offset:128
	global_load_dwordx4 v[48:51], v95, s[76:77] offset:192
	global_load_dwordx4 v[106:109], v95, s[78:79] offset:192
	s_mov_b64 exec, s[26:27]
	s_waitcnt vmcnt(32)
	s_mov_b64 exec, s[10:11]
	s_cbranch_execz .Ll2ci_skip_0_1
	v_pk_fma_f32 v[2:3], v[110:111], v[2:3], v[126:127]
	v_pk_mul_f32 v[56:57], v[56:57], v[110:111]
	v_pk_fma_f32 v[4:5], v[112:113], v[4:5], v[128:129]
	v_pk_mul_f32 v[58:59], v[58:59], v[112:113]
	v_pk_fma_f32 v[6:7], v[114:115], v[6:7], v[130:131]
	v_pk_mul_f32 v[60:61], v[60:61], v[114:115]
	v_pk_fma_f32 v[8:9], v[116:117], v[8:9], v[132:133]
	v_pk_mul_f32 v[62:63], v[62:63], v[116:117]
	v_pk_fma_f32 v[10:11], v[118:119], v[10:11], v[134:135]
	v_pk_mul_f32 v[64:65], v[64:65], v[118:119]
	v_pk_fma_f32 v[12:13], v[120:121], v[12:13], v[136:137]
	v_pk_mul_f32 v[66:67], v[66:67], v[120:121]
	v_pk_fma_f32 v[14:15], v[122:123], v[14:15], v[138:139]
	v_pk_mul_f32 v[68:69], v[68:69], v[122:123]
	v_pk_fma_f32 v[16:17], v[124:125], v[16:17], v[140:141]
	v_pk_mul_f32 v[70:71], v[70:71], v[124:125]
.Ll2ci_skip_0_1:
	s_mov_b64 exec, s[26:27]
	s_mov_b64 exec, s[20:21]
	global_load_dwordx4 v[110:113], v96, s[76:77] offset:0
	global_load_dwordx4 v[126:129], v96, s[78:79] offset:0
	global_load_dwordx4 v[114:117], v96, s[76:77] offset:64
	global_load_dwordx4 v[130:133], v96, s[78:79] offset:64
	global_load_dwordx4 v[118:121], v96, s[76:77] offset:128
	global_load_dwordx4 v[134:137], v96, s[78:79] offset:128
	global_load_dwordx4 v[122:125], v96, s[76:77] offset:192
	global_load_dwordx4 v[138:141], v96, s[78:79] offset:192
	s_mov_b64 exec, s[26:27]
	s_waitcnt vmcnt(32)
	s_mov_b64 exec, s[12:13]
	s_cbranch_execz .Ll2ci_skip_0_2
	v_pk_fma_f32 v[2:3], v[142:143], v[2:3], v[158:159]
	v_pk_mul_f32 v[56:57], v[56:57], v[142:143]
	v_pk_fma_f32 v[4:5], v[144:145], v[4:5], v[160:161]
	v_pk_mul_f32 v[58:59], v[58:59], v[144:145]
	v_pk_fma_f32 v[6:7], v[146:147], v[6:7], v[162:163]
	v_pk_mul_f32 v[60:61], v[60:61], v[146:147]
	v_pk_fma_f32 v[8:9], v[148:149], v[8:9], v[164:165]
	v_pk_mul_f32 v[62:63], v[62:63], v[148:149]
	v_pk_fma_f32 v[10:11], v[150:151], v[10:11], v[166:167]
	v_pk_mul_f32 v[64:65], v[64:65], v[150:151]
	v_pk_fma_f32 v[12:13], v[152:153], v[12:13], v[168:169]
	v_pk_mul_f32 v[66:67], v[66:67], v[152:153]
	v_pk_fma_f32 v[14:15], v[154:155], v[14:15], v[170:171]
	v_pk_mul_f32 v[68:69], v[68:69], v[154:155]
	v_pk_fma_f32 v[16:17], v[156:157], v[16:17], v[172:173]
	v_pk_mul_f32 v[70:71], v[70:71], v[156:157]
.Ll2ci_skip_0_2:
	s_mov_b64 exec, s[26:27]
	s_mov_b64 exec, s[22:23]
	global_load_dwordx4 v[142:145], v98, s[76:77] offset:0
	global_load_dwordx4 v[158:161], v98, s[78:79] offset:0
	global_load_dwordx4 v[146:149], v98, s[76:77] offset:64
	global_load_dwordx4 v[162:165], v98, s[78:79] offset:64
	global_load_dwordx4 v[150:153], v98, s[76:77] offset:128
	global_load_dwordx4 v[166:169], v98, s[78:79] offset:128
	global_load_dwordx4 v[154:157], v98, s[76:77] offset:192
	global_load_dwordx4 v[170:173], v98, s[78:79] offset:192
	s_mov_b64 exec, s[26:27]
	s_waitcnt vmcnt(32)
	s_mov_b64 exec, s[14:15]
	s_cbranch_execz .Ll2ci_skip_0_3
	v_pk_fma_f32 v[2:3], v[174:175], v[2:3], v[192:193]
	v_pk_mul_f32 v[56:57], v[56:57], v[174:175]
	v_pk_fma_f32 v[4:5], v[176:177], v[4:5], v[194:195]
	v_pk_mul_f32 v[58:59], v[58:59], v[176:177]
	v_pk_fma_f32 v[6:7], v[178:179], v[6:7], v[196:197]
	v_pk_mul_f32 v[60:61], v[60:61], v[178:179]
	v_pk_fma_f32 v[8:9], v[180:181], v[8:9], v[198:199]
	v_pk_mul_f32 v[62:63], v[62:63], v[180:181]
	v_pk_fma_f32 v[10:11], v[182:183], v[10:11], v[200:201]
	v_pk_mul_f32 v[64:65], v[64:65], v[182:183]
	v_pk_fma_f32 v[12:13], v[184:185], v[12:13], v[202:203]
	v_pk_mul_f32 v[66:67], v[66:67], v[184:185]
	v_pk_fma_f32 v[14:15], v[186:187], v[14:15], v[204:205]
	v_pk_mul_f32 v[68:69], v[68:69], v[186:187]
	v_pk_fma_f32 v[16:17], v[188:189], v[16:17], v[206:207]
	v_pk_mul_f32 v[70:71], v[70:71], v[188:189]
.Ll2ci_skip_0_3:
	s_mov_b64 exec, s[26:27]
	s_mov_b64 exec, s[24:25]
	global_load_dwordx4 v[174:177], v99, s[76:77] offset:0
	global_load_dwordx4 v[192:195], v99, s[78:79] offset:0
	global_load_dwordx4 v[178:181], v99, s[76:77] offset:64
	global_load_dwordx4 v[196:199], v99, s[78:79] offset:64
	global_load_dwordx4 v[182:185], v99, s[76:77] offset:128
	global_load_dwordx4 v[200:203], v99, s[78:79] offset:128
	global_load_dwordx4 v[186:189], v99, s[76:77] offset:192
	global_load_dwordx4 v[204:207], v99, s[78:79] offset:192
	s_mov_b64 exec, s[26:27]
	s_waitcnt vmcnt(32)
	s_mov_b64 exec, s[16:17]
	s_cbranch_execz .Ll2ci_skip_0_4
	v_pk_fma_f32 v[2:3], v[208:209], v[2:3], v[224:225]
	v_pk_mul_f32 v[56:57], v[56:57], v[208:209]
	v_pk_fma_f32 v[4:5], v[210:211], v[4:5], v[226:227]
	v_pk_mul_f32 v[58:59], v[58:59], v[210:211]
	v_pk_fma_f32 v[6:7], v[212:213], v[6:7], v[234:235]
	v_pk_mul_f32 v[60:61], v[60:61], v[212:213]
	v_pk_fma_f32 v[8:9], v[214:215], v[8:9], v[236:237]
	v_pk_mul_f32 v[62:63], v[62:63], v[214:215]
	v_pk_fma_f32 v[10:11], v[216:217], v[10:11], v[246:247]
	v_pk_mul_f32 v[64:65], v[64:65], v[216:217]
	v_pk_fma_f32 v[12:13], v[218:219], v[12:13], v[248:249]
	v_pk_mul_f32 v[66:67], v[66:67], v[218:219]
	v_pk_fma_f32 v[14:15], v[220:221], v[14:15], v[250:251]
	v_pk_mul_f32 v[68:69], v[68:69], v[220:221]
	v_pk_fma_f32 v[16:17], v[222:223], v[16:17], v[252:253]
	v_pk_mul_f32 v[70:71], v[70:71], v[222:223]
.Ll2ci_skip_0_4:
	s_mov_b64 exec, s[26:27]
	s_mov_b64 exec, s[58:59]
	global_load_dwordx4 v[208:211], v100, s[76:77] offset:0
	global_load_dwordx4 v[224:227], v100, s[78:79] offset:0
	global_load_dwordx4 v[212:215], v100, s[76:77] offset:64
	global_load_dwordx4 v[234:237], v100, s[78:79] offset:64
	global_load_dwordx4 v[216:219], v100, s[76:77] offset:128
	global_load_dwordx4 v[246:249], v100, s[78:79] offset:128
	global_load_dwordx4 v[220:223], v100, s[76:77] offset:192
	global_load_dwordx4 v[250:253], v100, s[78:79] offset:192
	s_mov_b64 exec, s[26:27]
	s_nop 4
	v_fmac_f32_dpp v2, v2, v56 row_shr:1 row_mask:0xf bank_mask:0xf bound_ctrl:1
	v_mul_f32_dpp v56, v56, v56 row_shr:1 row_mask:0xf bank_mask:0xf
	v_fmac_f32_dpp v3, v3, v57 row_shr:1 row_mask:0xf bank_mask:0xf bound_ctrl:1
	v_mul_f32_dpp v57, v57, v57 row_shr:1 row_mask:0xf bank_mask:0xf
	v_fmac_f32_dpp v4, v4, v58 row_shr:1 row_mask:0xf bank_mask:0xf bound_ctrl:1
	v_mul_f32_dpp v58, v58, v58 row_shr:1 row_mask:0xf bank_mask:0xf
	v_fmac_f32_dpp v5, v5, v59 row_shr:1 row_mask:0xf bank_mask:0xf bound_ctrl:1
	v_mul_f32_dpp v59, v59, v59 row_shr:1 row_mask:0xf bank_mask:0xf
	v_fmac_f32_dpp v6, v6, v60 row_shr:1 row_mask:0xf bank_mask:0xf bound_ctrl:1
	v_mul_f32_dpp v60, v60, v60 row_shr:1 row_mask:0xf bank_mask:0xf
	v_fmac_f32_dpp v7, v7, v61 row_shr:1 row_mask:0xf bank_mask:0xf bound_ctrl:1
	v_mul_f32_dpp v61, v61, v61 row_shr:1 row_mask:0xf bank_mask:0xf
	v_fmac_f32_dpp v8, v8, v62 row_shr:1 row_mask:0xf bank_mask:0xf bound_ctrl:1
	v_mul_f32_dpp v62, v62, v62 row_shr:1 row_mask:0xf bank_mask:0xf
	v_fmac_f32_dpp v9, v9, v63 row_shr:1 row_mask:0xf bank_mask:0xf bound_ctrl:1
	v_mul_f32_dpp v63, v63, v63 row_shr:1 row_mask:0xf bank_mask:0xf
	v_fmac_f32_dpp v10, v10, v64 row_shr:1 row_mask:0xf bank_mask:0xf bound_ctrl:1
	v_mul_f32_dpp v64, v64, v64 row_shr:1 row_mask:0xf bank_mask:0xf
	v_fmac_f32_dpp v11, v11, v65 row_shr:1 row_mask:0xf bank_mask:0xf bound_ctrl:1
	v_mul_f32_dpp v65, v65, v65 row_shr:1 row_mask:0xf bank_mask:0xf
	v_fmac_f32_dpp v12, v12, v66 row_shr:1 row_mask:0xf bank_mask:0xf bound_ctrl:1
	v_mul_f32_dpp v66, v66, v66 row_shr:1 row_mask:0xf bank_mask:0xf
	v_fmac_f32_dpp v13, v13, v67 row_shr:1 row_mask:0xf bank_mask:0xf bound_ctrl:1
	v_mul_f32_dpp v67, v67, v67 row_shr:1 row_mask:0xf bank_mask:0xf
	v_fmac_f32_dpp v14, v14, v68 row_shr:1 row_mask:0xf bank_mask:0xf bound_ctrl:1
	v_mul_f32_dpp v68, v68, v68 row_shr:1 row_mask:0xf bank_mask:0xf
	v_fmac_f32_dpp v15, v15, v69 row_shr:1 row_mask:0xf bank_mask:0xf bound_ctrl:1
	v_mul_f32_dpp v69, v69, v69 row_shr:1 row_mask:0xf bank_mask:0xf
	v_fmac_f32_dpp v16, v16, v70 row_shr:1 row_mask:0xf bank_mask:0xf bound_ctrl:1
	v_mul_f32_dpp v70, v70, v70 row_shr:1 row_mask:0xf bank_mask:0xf
	v_fmac_f32_dpp v17, v17, v71 row_shr:1 row_mask:0xf bank_mask:0xf bound_ctrl:1
	v_mul_f32_dpp v71, v71, v71 row_shr:1 row_mask:0xf bank_mask:0xf
	v_fmac_f32_dpp v2, v2, v56 row_shr:2 row_mask:0xf bank_mask:0xf bound_ctrl:1
	v_mul_f32_dpp v56, v56, v56 row_shr:2 row_mask:0xf bank_mask:0xf
	v_fmac_f32_dpp v3, v3, v57 row_shr:2 row_mask:0xf bank_mask:0xf bound_ctrl:1
	v_mul_f32_dpp v57, v57, v57 row_shr:2 row_mask:0xf bank_mask:0xf
	v_fmac_f32_dpp v4, v4, v58 row_shr:2 row_mask:0xf bank_mask:0xf bound_ctrl:1
	v_mul_f32_dpp v58, v58, v58 row_shr:2 row_mask:0xf bank_mask:0xf
	v_fmac_f32_dpp v5, v5, v59 row_shr:2 row_mask:0xf bank_mask:0xf bound_ctrl:1
	v_mul_f32_dpp v59, v59, v59 row_shr:2 row_mask:0xf bank_mask:0xf
	v_fmac_f32_dpp v6, v6, v60 row_shr:2 row_mask:0xf bank_mask:0xf bound_ctrl:1
	v_mul_f32_dpp v60, v60, v60 row_shr:2 row_mask:0xf bank_mask:0xf
	v_fmac_f32_dpp v7, v7, v61 row_shr:2 row_mask:0xf bank_mask:0xf bound_ctrl:1
	v_mul_f32_dpp v61, v61, v61 row_shr:2 row_mask:0xf bank_mask:0xf
	v_fmac_f32_dpp v8, v8, v62 row_shr:2 row_mask:0xf bank_mask:0xf bound_ctrl:1
	v_mul_f32_dpp v62, v62, v62 row_shr:2 row_mask:0xf bank_mask:0xf
	v_fmac_f32_dpp v9, v9, v63 row_shr:2 row_mask:0xf bank_mask:0xf bound_ctrl:1
	v_mul_f32_dpp v63, v63, v63 row_shr:2 row_mask:0xf bank_mask:0xf
	v_fmac_f32_dpp v10, v10, v64 row_shr:2 row_mask:0xf bank_mask:0xf bound_ctrl:1
	v_mul_f32_dpp v64, v64, v64 row_shr:2 row_mask:0xf bank_mask:0xf
	v_fmac_f32_dpp v11, v11, v65 row_shr:2 row_mask:0xf bank_mask:0xf bound_ctrl:1
	v_mul_f32_dpp v65, v65, v65 row_shr:2 row_mask:0xf bank_mask:0xf
	v_fmac_f32_dpp v12, v12, v66 row_shr:2 row_mask:0xf bank_mask:0xf bound_ctrl:1
	v_mul_f32_dpp v66, v66, v66 row_shr:2 row_mask:0xf bank_mask:0xf
	v_fmac_f32_dpp v13, v13, v67 row_shr:2 row_mask:0xf bank_mask:0xf bound_ctrl:1
	v_mul_f32_dpp v67, v67, v67 row_shr:2 row_mask:0xf bank_mask:0xf
	v_fmac_f32_dpp v14, v14, v68 row_shr:2 row_mask:0xf bank_mask:0xf bound_ctrl:1
	v_mul_f32_dpp v68, v68, v68 row_shr:2 row_mask:0xf bank_mask:0xf
	v_fmac_f32_dpp v15, v15, v69 row_shr:2 row_mask:0xf bank_mask:0xf bound_ctrl:1
	v_mul_f32_dpp v69, v69, v69 row_shr:2 row_mask:0xf bank_mask:0xf
	v_fmac_f32_dpp v16, v16, v70 row_shr:2 row_mask:0xf bank_mask:0xf bound_ctrl:1
	v_mul_f32_dpp v70, v70, v70 row_shr:2 row_mask:0xf bank_mask:0xf
	v_fmac_f32_dpp v17, v17, v71 row_shr:2 row_mask:0xf bank_mask:0xf bound_ctrl:1
	v_mul_f32_dpp v71, v71, v71 row_shr:2 row_mask:0xf bank_mask:0xf
	v_fmac_f32_dpp v2, v2, v56 row_shr:4 row_mask:0xf bank_mask:0xf bound_ctrl:1
	v_mul_f32_dpp v56, v56, v56 row_shr:4 row_mask:0xf bank_mask:0xf
	v_fmac_f32_dpp v3, v3, v57 row_shr:4 row_mask:0xf bank_mask:0xf bound_ctrl:1
	v_mul_f32_dpp v57, v57, v57 row_shr:4 row_mask:0xf bank_mask:0xf
	v_fmac_f32_dpp v4, v4, v58 row_shr:4 row_mask:0xf bank_mask:0xf bound_ctrl:1
	v_mul_f32_dpp v58, v58, v58 row_shr:4 row_mask:0xf bank_mask:0xf
	v_fmac_f32_dpp v5, v5, v59 row_shr:4 row_mask:0xf bank_mask:0xf bound_ctrl:1
	v_mul_f32_dpp v59, v59, v59 row_shr:4 row_mask:0xf bank_mask:0xf
	v_fmac_f32_dpp v6, v6, v60 row_shr:4 row_mask:0xf bank_mask:0xf bound_ctrl:1
	v_mul_f32_dpp v60, v60, v60 row_shr:4 row_mask:0xf bank_mask:0xf
	v_fmac_f32_dpp v7, v7, v61 row_shr:4 row_mask:0xf bank_mask:0xf bound_ctrl:1
	v_mul_f32_dpp v61, v61, v61 row_shr:4 row_mask:0xf bank_mask:0xf
	v_fmac_f32_dpp v8, v8, v62 row_shr:4 row_mask:0xf bank_mask:0xf bound_ctrl:1
	v_mul_f32_dpp v62, v62, v62 row_shr:4 row_mask:0xf bank_mask:0xf
	v_fmac_f32_dpp v9, v9, v63 row_shr:4 row_mask:0xf bank_mask:0xf bound_ctrl:1
	v_mul_f32_dpp v63, v63, v63 row_shr:4 row_mask:0xf bank_mask:0xf
	v_fmac_f32_dpp v10, v10, v64 row_shr:4 row_mask:0xf bank_mask:0xf bound_ctrl:1
	v_mul_f32_dpp v64, v64, v64 row_shr:4 row_mask:0xf bank_mask:0xf
	v_fmac_f32_dpp v11, v11, v65 row_shr:4 row_mask:0xf bank_mask:0xf bound_ctrl:1
	v_mul_f32_dpp v65, v65, v65 row_shr:4 row_mask:0xf bank_mask:0xf
	v_fmac_f32_dpp v12, v12, v66 row_shr:4 row_mask:0xf bank_mask:0xf bound_ctrl:1
	v_mul_f32_dpp v66, v66, v66 row_shr:4 row_mask:0xf bank_mask:0xf
	v_fmac_f32_dpp v13, v13, v67 row_shr:4 row_mask:0xf bank_mask:0xf bound_ctrl:1
	v_mul_f32_dpp v67, v67, v67 row_shr:4 row_mask:0xf bank_mask:0xf
	v_fmac_f32_dpp v14, v14, v68 row_shr:4 row_mask:0xf bank_mask:0xf bound_ctrl:1
	v_mul_f32_dpp v68, v68, v68 row_shr:4 row_mask:0xf bank_mask:0xf
	v_fmac_f32_dpp v15, v15, v69 row_shr:4 row_mask:0xf bank_mask:0xf bound_ctrl:1
	v_mul_f32_dpp v69, v69, v69 row_shr:4 row_mask:0xf bank_mask:0xf
	v_fmac_f32_dpp v16, v16, v70 row_shr:4 row_mask:0xf bank_mask:0xf bound_ctrl:1
	v_mul_f32_dpp v70, v70, v70 row_shr:4 row_mask:0xf bank_mask:0xf
	v_fmac_f32_dpp v17, v17, v71 row_shr:4 row_mask:0xf bank_mask:0xf bound_ctrl:1
	v_mul_f32_dpp v71, v71, v71 row_shr:4 row_mask:0xf bank_mask:0xf
	v_fmac_f32_dpp v2, v2, v56 row_shr:8 row_mask:0xf bank_mask:0xf bound_ctrl:1
	v_fmac_f32_dpp v3, v3, v57 row_shr:8 row_mask:0xf bank_mask:0xf bound_ctrl:1
	v_fmac_f32_dpp v4, v4, v58 row_shr:8 row_mask:0xf bank_mask:0xf bound_ctrl:1
	v_fmac_f32_dpp v5, v5, v59 row_shr:8 row_mask:0xf bank_mask:0xf bound_ctrl:1
	v_fmac_f32_dpp v6, v6, v60 row_shr:8 row_mask:0xf bank_mask:0xf bound_ctrl:1
	v_fmac_f32_dpp v7, v7, v61 row_shr:8 row_mask:0xf bank_mask:0xf bound_ctrl:1
	v_fmac_f32_dpp v8, v8, v62 row_shr:8 row_mask:0xf bank_mask:0xf bound_ctrl:1
	v_fmac_f32_dpp v9, v9, v63 row_shr:8 row_mask:0xf bank_mask:0xf bound_ctrl:1
	v_fmac_f32_dpp v10, v10, v64 row_shr:8 row_mask:0xf bank_mask:0xf bound_ctrl:1
	v_fmac_f32_dpp v11, v11, v65 row_shr:8 row_mask:0xf bank_mask:0xf bound_ctrl:1
	v_fmac_f32_dpp v12, v12, v66 row_shr:8 row_mask:0xf bank_mask:0xf bound_ctrl:1
	v_fmac_f32_dpp v13, v13, v67 row_shr:8 row_mask:0xf bank_mask:0xf bound_ctrl:1
	v_fmac_f32_dpp v14, v14, v68 row_shr:8 row_mask:0xf bank_mask:0xf bound_ctrl:1
	v_fmac_f32_dpp v15, v15, v69 row_shr:8 row_mask:0xf bank_mask:0xf bound_ctrl:1
	v_fmac_f32_dpp v16, v16, v70 row_shr:8 row_mask:0xf bank_mask:0xf bound_ctrl:1
	v_fmac_f32_dpp v17, v17, v71 row_shr:8 row_mask:0xf bank_mask:0xf bound_ctrl:1
	s_nop 1
	ds_bpermute_b32 v34, v245, v2
	ds_bpermute_b32 v35, v245, v3
	ds_bpermute_b32 v32, v245, v4
	ds_bpermute_b32 v33, v245, v5
	ds_bpermute_b32 v30, v245, v6
	ds_bpermute_b32 v31, v245, v7
	ds_bpermute_b32 v28, v245, v8
	ds_bpermute_b32 v29, v245, v9
	ds_bpermute_b32 v26, v245, v10
	ds_bpermute_b32 v27, v245, v11
	ds_bpermute_b32 v24, v245, v12
	ds_bpermute_b32 v25, v245, v13
	ds_bpermute_b32 v22, v245, v14
	ds_bpermute_b32 v23, v245, v15
	ds_bpermute_b32 v20, v245, v16
	ds_bpermute_b32 v21, v245, v17
	s_waitcnt vmcnt(32)
	v_cndmask_b32_e64 v56, 1.0, v36, s[18:19]
	v_cndmask_b32_e64 v2, 0, v84, s[18:19]
	v_cndmask_b32_e64 v57, 1.0, v37, s[18:19]
	v_cndmask_b32_e64 v3, 0, v85, s[18:19]
	v_cndmask_b32_e64 v58, 1.0, v38, s[18:19]
	v_cndmask_b32_e64 v4, 0, v86, s[18:19]
	v_cndmask_b32_e64 v59, 1.0, v39, s[18:19]
	v_cndmask_b32_e64 v5, 0, v87, s[18:19]
	v_cndmask_b32_e64 v60, 1.0, v40, s[18:19]
	v_cndmask_b32_e64 v6, 0, v88, s[18:19]
	v_cndmask_b32_e64 v61, 1.0, v41, s[18:19]
	v_cndmask_b32_e64 v7, 0, v89, s[18:19]
	v_cndmask_b32_e64 v62, 1.0, v42, s[18:19]
	v_cndmask_b32_e64 v8, 0, v90, s[18:19]
	v_cndmask_b32_e64 v63, 1.0, v43, s[18:19]
	v_cndmask_b32_e64 v9, 0, v91, s[18:19]
	v_cndmask_b32_e64 v64, 1.0, v44, s[18:19]
	v_cndmask_b32_e64 v10, 0, v102, s[18:19]
	v_cndmask_b32_e64 v65, 1.0, v45, s[18:19]
	v_cndmask_b32_e64 v11, 0, v103, s[18:19]
	v_cndmask_b32_e64 v66, 1.0, v46, s[18:19]
	v_cndmask_b32_e64 v12, 0, v104, s[18:19]
	v_cndmask_b32_e64 v67, 1.0, v47, s[18:19]
	v_cndmask_b32_e64 v13, 0, v105, s[18:19]
	v_cndmask_b32_e64 v68, 1.0, v48, s[18:19]
	v_cndmask_b32_e64 v14, 0, v106, s[18:19]
	v_cndmask_b32_e64 v69, 1.0, v49, s[18:19]
	v_cndmask_b32_e64 v15, 0, v107, s[18:19]
	v_cndmask_b32_e64 v70, 1.0, v50, s[18:19]
	v_cndmask_b32_e64 v16, 0, v108, s[18:19]
	v_cndmask_b32_e64 v71, 1.0, v51, s[18:19]
	v_cndmask_b32_e64 v17, 0, v109, s[18:19]
	s_waitcnt vmcnt(24)
	s_mov_b64 exec, s[20:21]
	s_cbranch_execz .Ll2ci_skip_1_1
	v_pk_fma_f32 v[2:3], v[110:111], v[2:3], v[126:127]
	v_pk_mul_f32 v[56:57], v[56:57], v[110:111]
	v_pk_fma_f32 v[4:5], v[112:113], v[4:5], v[128:129]
	v_pk_mul_f32 v[58:59], v[58:59], v[112:113]
	v_pk_fma_f32 v[6:7], v[114:115], v[6:7], v[130:131]
	v_pk_mul_f32 v[60:61], v[60:61], v[114:115]
	v_pk_fma_f32 v[8:9], v[116:117], v[8:9], v[132:133]
	v_pk_mul_f32 v[62:63], v[62:63], v[116:117]
	v_pk_fma_f32 v[10:11], v[118:119], v[10:11], v[134:135]
	v_pk_mul_f32 v[64:65], v[64:65], v[118:119]
	v_pk_fma_f32 v[12:13], v[120:121], v[12:13], v[136:137]
	v_pk_mul_f32 v[66:67], v[66:67], v[120:121]
	v_pk_fma_f32 v[14:15], v[122:123], v[14:15], v[138:139]
	v_pk_mul_f32 v[68:69], v[68:69], v[122:123]
	v_pk_fma_f32 v[16:17], v[124:125], v[16:17], v[140:141]
	v_pk_mul_f32 v[70:71], v[70:71], v[124:125]
.Ll2ci_skip_1_1:
	s_mov_b64 exec, s[26:27]
	s_waitcnt vmcnt(16)
	s_mov_b64 exec, s[22:23]
	s_cbranch_execz .Ll2ci_skip_1_2
	v_pk_fma_f32 v[2:3], v[142:143], v[2:3], v[158:159]
	v_pk_mul_f32 v[56:57], v[56:57], v[142:143]
	v_pk_fma_f32 v[4:5], v[144:145], v[4:5], v[160:161]
	v_pk_mul_f32 v[58:59], v[58:59], v[144:145]
	v_pk_fma_f32 v[6:7], v[146:147], v[6:7], v[162:163]
	v_pk_mul_f32 v[60:61], v[60:61], v[146:147]
	v_pk_fma_f32 v[8:9], v[148:149], v[8:9], v[164:165]
	v_pk_mul_f32 v[62:63], v[62:63], v[148:149]
	v_pk_fma_f32 v[10:11], v[150:151], v[10:11], v[166:167]
	v_pk_mul_f32 v[64:65], v[64:65], v[150:151]
	v_pk_fma_f32 v[12:13], v[152:153], v[12:13], v[168:169]
	v_pk_mul_f32 v[66:67], v[66:67], v[152:153]
	v_pk_fma_f32 v[14:15], v[154:155], v[14:15], v[170:171]
	v_pk_mul_f32 v[68:69], v[68:69], v[154:155]
	v_pk_fma_f32 v[16:17], v[156:157], v[16:17], v[172:173]
	v_pk_mul_f32 v[70:71], v[70:71], v[156:157]
.Ll2ci_skip_1_2:
	s_mov_b64 exec, s[26:27]
	s_waitcnt vmcnt(8)
	s_mov_b64 exec, s[24:25]
	s_cbranch_execz .Ll2ci_skip_1_3
	v_pk_fma_f32 v[2:3], v[174:175], v[2:3], v[192:193]
	v_pk_mul_f32 v[56:57], v[56:57], v[174:175]
	v_pk_fma_f32 v[4:5], v[176:177], v[4:5], v[194:195]
	v_pk_mul_f32 v[58:59], v[58:59], v[176:177]
	v_pk_fma_f32 v[6:7], v[178:179], v[6:7], v[196:197]
	v_pk_mul_f32 v[60:61], v[60:61], v[178:179]
	v_pk_fma_f32 v[8:9], v[180:181], v[8:9], v[198:199]
	v_pk_mul_f32 v[62:63], v[62:63], v[180:181]
	v_pk_fma_f32 v[10:11], v[182:183], v[10:11], v[200:201]
	v_pk_mul_f32 v[64:65], v[64:65], v[182:183]
	v_pk_fma_f32 v[12:13], v[184:185], v[12:13], v[202:203]
	v_pk_mul_f32 v[66:67], v[66:67], v[184:185]
	v_pk_fma_f32 v[14:15], v[186:187], v[14:15], v[204:205]
	v_pk_mul_f32 v[68:69], v[68:69], v[186:187]
	v_pk_fma_f32 v[16:17], v[188:189], v[16:17], v[206:207]
	v_pk_mul_f32 v[70:71], v[70:71], v[188:189]
.Ll2ci_skip_1_3:
	s_mov_b64 exec, s[26:27]
	s_waitcnt vmcnt(0)
	s_mov_b64 exec, s[58:59]
	s_cbranch_execz .Ll2ci_skip_1_4
	v_pk_fma_f32 v[2:3], v[208:209], v[2:3], v[224:225]
	v_pk_mul_f32 v[56:57], v[56:57], v[208:209]
	v_pk_fma_f32 v[4:5], v[210:211], v[4:5], v[226:227]
	v_pk_mul_f32 v[58:59], v[58:59], v[210:211]
	v_pk_fma_f32 v[6:7], v[212:213], v[6:7], v[234:235]
	v_pk_mul_f32 v[60:61], v[60:61], v[212:213]
	v_pk_fma_f32 v[8:9], v[214:215], v[8:9], v[236:237]
	v_pk_mul_f32 v[62:63], v[62:63], v[214:215]
	v_pk_fma_f32 v[10:11], v[216:217], v[10:11], v[246:247]
	v_pk_mul_f32 v[64:65], v[64:65], v[216:217]
	v_pk_fma_f32 v[12:13], v[218:219], v[12:13], v[248:249]
	v_pk_mul_f32 v[66:67], v[66:67], v[218:219]
	v_pk_fma_f32 v[14:15], v[220:221], v[14:15], v[250:251]
	v_pk_mul_f32 v[68:69], v[68:69], v[220:221]
	v_pk_fma_f32 v[16:17], v[222:223], v[16:17], v[252:253]
	v_pk_mul_f32 v[70:71], v[70:71], v[222:223]
.Ll2ci_skip_1_4:
	s_mov_b64 exec, s[26:27]
	s_nop 4
	v_fmac_f32_dpp v2, v2, v56 row_shr:1 row_mask:0xf bank_mask:0xf bound_ctrl:1
	v_mul_f32_dpp v56, v56, v56 row_shr:1 row_mask:0xf bank_mask:0xf
	v_fmac_f32_dpp v3, v3, v57 row_shr:1 row_mask:0xf bank_mask:0xf bound_ctrl:1
	v_mul_f32_dpp v57, v57, v57 row_shr:1 row_mask:0xf bank_mask:0xf
	v_fmac_f32_dpp v4, v4, v58 row_shr:1 row_mask:0xf bank_mask:0xf bound_ctrl:1
	v_mul_f32_dpp v58, v58, v58 row_shr:1 row_mask:0xf bank_mask:0xf
	v_fmac_f32_dpp v5, v5, v59 row_shr:1 row_mask:0xf bank_mask:0xf bound_ctrl:1
	v_mul_f32_dpp v59, v59, v59 row_shr:1 row_mask:0xf bank_mask:0xf
	v_fmac_f32_dpp v6, v6, v60 row_shr:1 row_mask:0xf bank_mask:0xf bound_ctrl:1
	v_mul_f32_dpp v60, v60, v60 row_shr:1 row_mask:0xf bank_mask:0xf
	v_fmac_f32_dpp v7, v7, v61 row_shr:1 row_mask:0xf bank_mask:0xf bound_ctrl:1
	v_mul_f32_dpp v61, v61, v61 row_shr:1 row_mask:0xf bank_mask:0xf
	v_fmac_f32_dpp v8, v8, v62 row_shr:1 row_mask:0xf bank_mask:0xf bound_ctrl:1
	v_mul_f32_dpp v62, v62, v62 row_shr:1 row_mask:0xf bank_mask:0xf
	v_fmac_f32_dpp v9, v9, v63 row_shr:1 row_mask:0xf bank_mask:0xf bound_ctrl:1
	v_mul_f32_dpp v63, v63, v63 row_shr:1 row_mask:0xf bank_mask:0xf
	v_fmac_f32_dpp v10, v10, v64 row_shr:1 row_mask:0xf bank_mask:0xf bound_ctrl:1
	v_mul_f32_dpp v64, v64, v64 row_shr:1 row_mask:0xf bank_mask:0xf
	v_fmac_f32_dpp v11, v11, v65 row_shr:1 row_mask:0xf bank_mask:0xf bound_ctrl:1
	v_mul_f32_dpp v65, v65, v65 row_shr:1 row_mask:0xf bank_mask:0xf
	v_fmac_f32_dpp v12, v12, v66 row_shr:1 row_mask:0xf bank_mask:0xf bound_ctrl:1
	v_mul_f32_dpp v66, v66, v66 row_shr:1 row_mask:0xf bank_mask:0xf
	v_fmac_f32_dpp v13, v13, v67 row_shr:1 row_mask:0xf bank_mask:0xf bound_ctrl:1
	v_mul_f32_dpp v67, v67, v67 row_shr:1 row_mask:0xf bank_mask:0xf
	v_fmac_f32_dpp v14, v14, v68 row_shr:1 row_mask:0xf bank_mask:0xf bound_ctrl:1
	v_mul_f32_dpp v68, v68, v68 row_shr:1 row_mask:0xf bank_mask:0xf
	v_fmac_f32_dpp v15, v15, v69 row_shr:1 row_mask:0xf bank_mask:0xf bound_ctrl:1
	v_mul_f32_dpp v69, v69, v69 row_shr:1 row_mask:0xf bank_mask:0xf
	v_fmac_f32_dpp v16, v16, v70 row_shr:1 row_mask:0xf bank_mask:0xf bound_ctrl:1
	v_mul_f32_dpp v70, v70, v70 row_shr:1 row_mask:0xf bank_mask:0xf
	v_fmac_f32_dpp v17, v17, v71 row_shr:1 row_mask:0xf bank_mask:0xf bound_ctrl:1
	v_mul_f32_dpp v71, v71, v71 row_shr:1 row_mask:0xf bank_mask:0xf
	v_fmac_f32_dpp v2, v2, v56 row_shr:2 row_mask:0xf bank_mask:0xf bound_ctrl:1
	v_mul_f32_dpp v56, v56, v56 row_shr:2 row_mask:0xf bank_mask:0xf
	v_fmac_f32_dpp v3, v3, v57 row_shr:2 row_mask:0xf bank_mask:0xf bound_ctrl:1
	v_mul_f32_dpp v57, v57, v57 row_shr:2 row_mask:0xf bank_mask:0xf
	v_fmac_f32_dpp v4, v4, v58 row_shr:2 row_mask:0xf bank_mask:0xf bound_ctrl:1
	v_mul_f32_dpp v58, v58, v58 row_shr:2 row_mask:0xf bank_mask:0xf
	v_fmac_f32_dpp v5, v5, v59 row_shr:2 row_mask:0xf bank_mask:0xf bound_ctrl:1
	v_mul_f32_dpp v59, v59, v59 row_shr:2 row_mask:0xf bank_mask:0xf
	v_fmac_f32_dpp v6, v6, v60 row_shr:2 row_mask:0xf bank_mask:0xf bound_ctrl:1
	v_mul_f32_dpp v60, v60, v60 row_shr:2 row_mask:0xf bank_mask:0xf
	v_fmac_f32_dpp v7, v7, v61 row_shr:2 row_mask:0xf bank_mask:0xf bound_ctrl:1
	v_mul_f32_dpp v61, v61, v61 row_shr:2 row_mask:0xf bank_mask:0xf
	v_fmac_f32_dpp v8, v8, v62 row_shr:2 row_mask:0xf bank_mask:0xf bound_ctrl:1
	v_mul_f32_dpp v62, v62, v62 row_shr:2 row_mask:0xf bank_mask:0xf
	v_fmac_f32_dpp v9, v9, v63 row_shr:2 row_mask:0xf bank_mask:0xf bound_ctrl:1
	v_mul_f32_dpp v63, v63, v63 row_shr:2 row_mask:0xf bank_mask:0xf
	v_fmac_f32_dpp v10, v10, v64 row_shr:2 row_mask:0xf bank_mask:0xf bound_ctrl:1
	v_mul_f32_dpp v64, v64, v64 row_shr:2 row_mask:0xf bank_mask:0xf
	v_fmac_f32_dpp v11, v11, v65 row_shr:2 row_mask:0xf bank_mask:0xf bound_ctrl:1
	v_mul_f32_dpp v65, v65, v65 row_shr:2 row_mask:0xf bank_mask:0xf
	v_fmac_f32_dpp v12, v12, v66 row_shr:2 row_mask:0xf bank_mask:0xf bound_ctrl:1
	v_mul_f32_dpp v66, v66, v66 row_shr:2 row_mask:0xf bank_mask:0xf
	v_fmac_f32_dpp v13, v13, v67 row_shr:2 row_mask:0xf bank_mask:0xf bound_ctrl:1
	v_mul_f32_dpp v67, v67, v67 row_shr:2 row_mask:0xf bank_mask:0xf
	v_fmac_f32_dpp v14, v14, v68 row_shr:2 row_mask:0xf bank_mask:0xf bound_ctrl:1
	v_mul_f32_dpp v68, v68, v68 row_shr:2 row_mask:0xf bank_mask:0xf
	v_fmac_f32_dpp v15, v15, v69 row_shr:2 row_mask:0xf bank_mask:0xf bound_ctrl:1
	v_mul_f32_dpp v69, v69, v69 row_shr:2 row_mask:0xf bank_mask:0xf
	v_fmac_f32_dpp v16, v16, v70 row_shr:2 row_mask:0xf bank_mask:0xf bound_ctrl:1
	v_mul_f32_dpp v70, v70, v70 row_shr:2 row_mask:0xf bank_mask:0xf
	v_fmac_f32_dpp v17, v17, v71 row_shr:2 row_mask:0xf bank_mask:0xf bound_ctrl:1
	v_mul_f32_dpp v71, v71, v71 row_shr:2 row_mask:0xf bank_mask:0xf
	v_fmac_f32_dpp v2, v2, v56 row_shr:4 row_mask:0xf bank_mask:0xf bound_ctrl:1
	v_mul_f32_dpp v56, v56, v56 row_shr:4 row_mask:0xf bank_mask:0xf
	v_fmac_f32_dpp v3, v3, v57 row_shr:4 row_mask:0xf bank_mask:0xf bound_ctrl:1
	v_mul_f32_dpp v57, v57, v57 row_shr:4 row_mask:0xf bank_mask:0xf
	v_fmac_f32_dpp v4, v4, v58 row_shr:4 row_mask:0xf bank_mask:0xf bound_ctrl:1
	v_mul_f32_dpp v58, v58, v58 row_shr:4 row_mask:0xf bank_mask:0xf
	v_fmac_f32_dpp v5, v5, v59 row_shr:4 row_mask:0xf bank_mask:0xf bound_ctrl:1
	v_mul_f32_dpp v59, v59, v59 row_shr:4 row_mask:0xf bank_mask:0xf
	v_fmac_f32_dpp v6, v6, v60 row_shr:4 row_mask:0xf bank_mask:0xf bound_ctrl:1
	v_mul_f32_dpp v60, v60, v60 row_shr:4 row_mask:0xf bank_mask:0xf
	v_fmac_f32_dpp v7, v7, v61 row_shr:4 row_mask:0xf bank_mask:0xf bound_ctrl:1
	v_mul_f32_dpp v61, v61, v61 row_shr:4 row_mask:0xf bank_mask:0xf
	v_fmac_f32_dpp v8, v8, v62 row_shr:4 row_mask:0xf bank_mask:0xf bound_ctrl:1
	v_mul_f32_dpp v62, v62, v62 row_shr:4 row_mask:0xf bank_mask:0xf
	v_fmac_f32_dpp v9, v9, v63 row_shr:4 row_mask:0xf bank_mask:0xf bound_ctrl:1
	v_mul_f32_dpp v63, v63, v63 row_shr:4 row_mask:0xf bank_mask:0xf
	v_fmac_f32_dpp v10, v10, v64 row_shr:4 row_mask:0xf bank_mask:0xf bound_ctrl:1
	v_mul_f32_dpp v64, v64, v64 row_shr:4 row_mask:0xf bank_mask:0xf
	v_fmac_f32_dpp v11, v11, v65 row_shr:4 row_mask:0xf bank_mask:0xf bound_ctrl:1
	v_mul_f32_dpp v65, v65, v65 row_shr:4 row_mask:0xf bank_mask:0xf
	v_fmac_f32_dpp v12, v12, v66 row_shr:4 row_mask:0xf bank_mask:0xf bound_ctrl:1
	v_mul_f32_dpp v66, v66, v66 row_shr:4 row_mask:0xf bank_mask:0xf
	v_fmac_f32_dpp v13, v13, v67 row_shr:4 row_mask:0xf bank_mask:0xf bound_ctrl:1
	v_mul_f32_dpp v67, v67, v67 row_shr:4 row_mask:0xf bank_mask:0xf
	v_fmac_f32_dpp v14, v14, v68 row_shr:4 row_mask:0xf bank_mask:0xf bound_ctrl:1
	v_mul_f32_dpp v68, v68, v68 row_shr:4 row_mask:0xf bank_mask:0xf
	v_fmac_f32_dpp v15, v15, v69 row_shr:4 row_mask:0xf bank_mask:0xf bound_ctrl:1
	v_mul_f32_dpp v69, v69, v69 row_shr:4 row_mask:0xf bank_mask:0xf
	v_fmac_f32_dpp v16, v16, v70 row_shr:4 row_mask:0xf bank_mask:0xf bound_ctrl:1
	v_mul_f32_dpp v70, v70, v70 row_shr:4 row_mask:0xf bank_mask:0xf
	v_fmac_f32_dpp v17, v17, v71 row_shr:4 row_mask:0xf bank_mask:0xf bound_ctrl:1
	v_mul_f32_dpp v71, v71, v71 row_shr:4 row_mask:0xf bank_mask:0xf
	v_fmac_f32_dpp v2, v2, v56 row_shr:8 row_mask:0xf bank_mask:0xf bound_ctrl:1
	v_fmac_f32_dpp v3, v3, v57 row_shr:8 row_mask:0xf bank_mask:0xf bound_ctrl:1
	v_fmac_f32_dpp v4, v4, v58 row_shr:8 row_mask:0xf bank_mask:0xf bound_ctrl:1
	v_fmac_f32_dpp v5, v5, v59 row_shr:8 row_mask:0xf bank_mask:0xf bound_ctrl:1
	v_fmac_f32_dpp v6, v6, v60 row_shr:8 row_mask:0xf bank_mask:0xf bound_ctrl:1
	v_fmac_f32_dpp v7, v7, v61 row_shr:8 row_mask:0xf bank_mask:0xf bound_ctrl:1
	v_fmac_f32_dpp v8, v8, v62 row_shr:8 row_mask:0xf bank_mask:0xf bound_ctrl:1
	v_fmac_f32_dpp v9, v9, v63 row_shr:8 row_mask:0xf bank_mask:0xf bound_ctrl:1
	v_fmac_f32_dpp v10, v10, v64 row_shr:8 row_mask:0xf bank_mask:0xf bound_ctrl:1
	v_fmac_f32_dpp v11, v11, v65 row_shr:8 row_mask:0xf bank_mask:0xf bound_ctrl:1
	v_fmac_f32_dpp v12, v12, v66 row_shr:8 row_mask:0xf bank_mask:0xf bound_ctrl:1
	v_fmac_f32_dpp v13, v13, v67 row_shr:8 row_mask:0xf bank_mask:0xf bound_ctrl:1
	v_fmac_f32_dpp v14, v14, v68 row_shr:8 row_mask:0xf bank_mask:0xf bound_ctrl:1
	v_fmac_f32_dpp v15, v15, v69 row_shr:8 row_mask:0xf bank_mask:0xf bound_ctrl:1
	v_fmac_f32_dpp v16, v16, v70 row_shr:8 row_mask:0xf bank_mask:0xf bound_ctrl:1
	v_fmac_f32_dpp v17, v17, v71 row_shr:8 row_mask:0xf bank_mask:0xf bound_ctrl:1
	s_nop 1
	ds_bpermute_b32 v36, v245, v2
	ds_bpermute_b32 v37, v245, v3
	ds_bpermute_b32 v38, v245, v4
	ds_bpermute_b32 v39, v245, v5
	ds_bpermute_b32 v40, v245, v6
	ds_bpermute_b32 v41, v245, v7
	ds_bpermute_b32 v42, v245, v8
	ds_bpermute_b32 v43, v245, v9
	ds_bpermute_b32 v44, v245, v10
	ds_bpermute_b32 v45, v245, v11
	ds_bpermute_b32 v46, v245, v12
	ds_bpermute_b32 v47, v245, v13
	ds_bpermute_b32 v48, v245, v14
	ds_bpermute_b32 v49, v245, v15
	ds_bpermute_b32 v50, v245, v16
	ds_bpermute_b32 v51, v245, v17
